# Loop-edge edit (asm guide 7.12): softmax rescale branch tests in cmp/sel/window/dilated loops reduced from exec-mask ballot chains to two compares plus scalar mask ops; on top of v31
# speedup vs baseline: 1.0131x; 1.0043x over previous
; DI float fast_exp2(float x) { return __builtin_amdgcn_exp2f(x); }
; DI float xhalf_max(float v) { const auto rr = __builtin_amdgcn_permlane32_swap(__float_as_uint(v), __float_as_uint(v), false, false); return fmaxf(__uint_as_float(rr[0]), __uint_as_float(rr[1])); }
; DI float soft_update(Soft& f, f32x16& x0, f32x16& x1, bool hasO) {
;     float ma = fmaxf(fmaxf(x0[0], x1[0]), x0[1]), mb = fmaxf(fmaxf(x1[1], x0[2]), x1[2]);
; #pragma unroll
;     for (int r = 3; r < 15; r += 2) { ma = fmaxf(fmaxf(ma, x0[r]), x1[r]); mb = fmaxf(fmaxf(mb, x0[r + 1]), x1[r + 1]); }
;     ma = fmaxf(fmaxf(ma, x0[15]), x1[15]);
;     float mx = xhalf_max(fmaxf(ma, mb));
;     const bool valid = mx > -1e20f;
;     const bool need = valid && (mx > 8.f || !f.seen);
;     float dmove = 0.f;
;     if (__builtin_amdgcn_ballot_w64(need)) {
;         const float delta = need ? fmaxf(mx, -60.f) : 0.f; const float sc = fast_exp2(-delta);
;         dmove = delta;
;         f.mref += delta; f.l *= sc;
;         if (hasO) {
; #pragma unroll
;             for (int r = 0; r < 16; ++r) { f.o0[r] *= sc; f.o1[r] *= sc; } }
; #pragma unroll
;         for (int r = 0; r < 16; ++r) { x0[r] -= delta; x1[r] -= delta; }
;     }
.LBB0_917:
	s_nop 10
	v_max_f32_e32 v1, v64, v64
	v_max_f32_e32 v14, v48, v48
	v_max_f32_e32 v1, v14, v1
	v_max3_f32 v14, v65, v50, v66
	v_max3_f32 v1, v1, v49, v51
	v_max3_f32 v14, v14, v52, v68
	v_max3_f32 v1, v1, v67, v53
	v_max3_f32 v14, v14, v54, v70
	v_max3_f32 v1, v1, v69, v55
	v_max3_f32 v14, v14, v56, v72
	v_max3_f32 v1, v1, v71, v57
	v_max3_f32 v14, v14, v58, v74
	v_max3_f32 v1, v1, v73, v59
	v_max3_f32 v14, v14, v60, v76
	v_max3_f32 v1, v1, v75, v61
	v_max3_f32 v14, v14, v62, v78
	v_max3_f32 v1, v1, v77, v63
	v_max3_f32 v1, v1, v79, v14
	v_mov_b32_e32 v14, v1
	s_nop 1
	v_permlane32_swap_b32_e32 v1, v14
	v_max_f32_e32 v14, v14, v14
	v_max_f32_e32 v1, v1, v1
	v_max_f32_e32 v1, v1, v14
	v_cmp_lt_f32_e64 s[6:7], s70, v1
	v_cmp_lt_f32_e64 s[4:5], s84, v1
	s_orn2_b64 s[4:5], s[4:5], s[42:43]
	s_and_b64 s[4:5], s[4:5], s[6:7]
	s_cbranch_scc0 .LBB0_923
	v_max_f32_e32 v1, v1, v1
	v_max_f32_e32 v1, 0xc2700000, v1
	v_cndmask_b32_e64 v14, 0, v1, s[4:5]
	v_exp_f32_e64 v132, -v14
	v_add_f32_e32 v131, v131, v14
	v_pk_add_f32 v[48:49], v[48:49], v[14:15] op_sel_hi:[1,0] neg_lo:[0,1] neg_hi:[0,1]
	v_pk_add_f32 v[64:65], v[64:65], v[14:15] op_sel_hi:[1,0] neg_lo:[0,1] neg_hi:[0,1]
	v_mul_f32_e32 v127, v127, v132
	v_pk_mul_f32 v[46:47], v[46:47], v[132:133] op_sel_hi:[1,0]
	v_pk_mul_f32 v[44:45], v[44:45], v[132:133] op_sel_hi:[1,0]
	v_pk_mul_f32 v[42:43], v[42:43], v[132:133] op_sel_hi:[1,0]
	v_pk_mul_f32 v[40:41], v[40:41], v[132:133] op_sel_hi:[1,0]
	v_pk_mul_f32 v[38:39], v[38:39], v[132:133] op_sel_hi:[1,0]
	v_pk_mul_f32 v[36:37], v[36:37], v[132:133] op_sel_hi:[1,0]
	v_pk_mul_f32 v[34:35], v[34:35], v[132:133] op_sel_hi:[1,0]
	v_pk_mul_f32 v[32:33], v[32:33], v[132:133] op_sel_hi:[1,0]
	v_pk_mul_f32 v[30:31], v[30:31], v[132:133] op_sel_hi:[1,0]
	v_pk_mul_f32 v[28:29], v[28:29], v[132:133] op_sel_hi:[1,0]
	v_pk_mul_f32 v[26:27], v[26:27], v[132:133] op_sel_hi:[1,0]
	v_pk_mul_f32 v[24:25], v[24:25], v[132:133] op_sel_hi:[1,0]
	v_pk_mul_f32 v[22:23], v[22:23], v[132:133] op_sel_hi:[1,0]
	v_pk_mul_f32 v[20:21], v[20:21], v[132:133] op_sel_hi:[1,0]
	v_pk_mul_f32 v[18:19], v[18:19], v[132:133] op_sel_hi:[1,0]
	v_pk_mul_f32 v[16:17], v[16:17], v[132:133] op_sel_hi:[1,0]
	v_pk_add_f32 v[50:51], v[50:51], v[14:15] op_sel_hi:[1,0] neg_lo:[0,1] neg_hi:[0,1]
	v_pk_add_f32 v[66:67], v[66:67], v[14:15] op_sel_hi:[1,0] neg_lo:[0,1] neg_hi:[0,1]
	v_pk_add_f32 v[52:53], v[52:53], v[14:15] op_sel_hi:[1,0] neg_lo:[0,1] neg_hi:[0,1]
	v_pk_add_f32 v[68:69], v[68:69], v[14:15] op_sel_hi:[1,0] neg_lo:[0,1] neg_hi:[0,1]
	v_pk_add_f32 v[54:55], v[54:55], v[14:15] op_sel_hi:[1,0] neg_lo:[0,1] neg_hi:[0,1]
	v_pk_add_f32 v[70:71], v[70:71], v[14:15] op_sel_hi:[1,0] neg_lo:[0,1] neg_hi:[0,1]
	v_pk_add_f32 v[56:57], v[56:57], v[14:15] op_sel_hi:[1,0] neg_lo:[0,1] neg_hi:[0,1]
	v_pk_add_f32 v[72:73], v[72:73], v[14:15] op_sel_hi:[1,0] neg_lo:[0,1] neg_hi:[0,1]
	v_pk_add_f32 v[58:59], v[58:59], v[14:15] op_sel_hi:[1,0] neg_lo:[0,1] neg_hi:[0,1]
	v_pk_add_f32 v[74:75], v[74:75], v[14:15] op_sel_hi:[1,0] neg_lo:[0,1] neg_hi:[0,1]
	v_pk_add_f32 v[60:61], v[60:61], v[14:15] op_sel_hi:[1,0] neg_lo:[0,1] neg_hi:[0,1]
	v_pk_add_f32 v[76:77], v[76:77], v[14:15] op_sel_hi:[1,0] neg_lo:[0,1] neg_hi:[0,1]
	v_pk_add_f32 v[62:63], v[62:63], v[14:15] op_sel_hi:[1,0] neg_lo:[0,1] neg_hi:[0,1]
	v_pk_add_f32 v[78:79], v[78:79], v[14:15] op_sel_hi:[1,0] neg_lo:[0,1] neg_hi:[0,1]
	s_branch .LBB0_924

; DI float fast_exp2(float x) { return __builtin_amdgcn_exp2f(x); }
; DI void nsa_unit(const bf16* PR, const bf16* VT, const bf16* kcb, const bf16* vctb, bf16* Y, LAS unsigned char* lds, int b, int g, int jt) {
;     ...
;                 const bool had = f.seen;
;                 const float dl = soft_update(f, x0, x1, true);
;                 if (__builtin_amdgcn_ballot_w64(had && dl != 0.f)) {
;                     const float sc = (had && dl != 0.f) ? fast_exp2(-dl) : 1.f;
;                     for (int j = hi; j < 128; j += 2) impw[j] *= sc;
;                 }
.LBB0_924:
	v_cmp_neq_f32_e32 vcc, 0, v14
	s_and_b64 s[8:9], s[42:43], vcc
	s_cbranch_scc0 .LBB0_926
	v_exp_f32_e64 v1, -v14
	ds_read2_b32 v[132:133], v125 offset1:2
	ds_read2_b32 v[134:135], v125 offset0:4 offset1:6
	ds_read2_b32 v[136:137], v125 offset0:8 offset1:10
	ds_read2_b32 v[138:139], v125 offset0:12 offset1:14
	v_cndmask_b32_e64 v14, 1.0, v1, s[8:9]
	s_waitcnt lgkmcnt(3)
	v_pk_mul_f32 v[132:133], v[14:15], v[132:133] op_sel_hi:[0,1]
	ds_write2_b32 v125, v132, v133 offset1:2
	s_waitcnt lgkmcnt(3)
	v_pk_mul_f32 v[132:133], v[14:15], v[134:135] op_sel_hi:[0,1]
	ds_read2_b32 v[134:135], v125 offset0:16 offset1:18
	ds_write2_b32 v125, v132, v133 offset0:4 offset1:6
	s_waitcnt lgkmcnt(4)
	v_pk_mul_f32 v[132:133], v[14:15], v[136:137] op_sel_hi:[0,1]
	ds_write2_b32 v125, v132, v133 offset0:8 offset1:10
	s_waitcnt lgkmcnt(4)
	v_pk_mul_f32 v[132:133], v[14:15], v[138:139] op_sel_hi:[0,1]
	ds_read2_b32 v[136:137], v125 offset0:20 offset1:22
	ds_write2_b32 v125, v132, v133 offset0:12 offset1:14
	s_waitcnt lgkmcnt(4)
	v_pk_mul_f32 v[132:133], v[14:15], v[134:135] op_sel_hi:[0,1]
	ds_read2_b32 v[134:135], v125 offset0:24 offset1:26
	ds_write2_b32 v125, v132, v133 offset0:16 offset1:18
	s_waitcnt lgkmcnt(3)
	v_pk_mul_f32 v[132:133], v[14:15], v[136:137] op_sel_hi:[0,1]
	ds_read2_b32 v[136:137], v125 offset0:28 offset1:30
	ds_write2_b32 v125, v132, v133 offset0:20 offset1:22
	s_waitcnt lgkmcnt(3)
	v_pk_mul_f32 v[132:133], v[14:15], v[134:135] op_sel_hi:[0,1]
	ds_read2_b32 v[134:135], v125 offset0:32 offset1:34
	ds_write2_b32 v125, v132, v133 offset0:24 offset1:26
	s_waitcnt lgkmcnt(3)
	v_pk_mul_f32 v[132:133], v[14:15], v[136:137] op_sel_hi:[0,1]
	ds_read2_b32 v[136:137], v125 offset0:36 offset1:38
	ds_write2_b32 v125, v132, v133 offset0:28 offset1:30
	s_waitcnt lgkmcnt(3)
	v_pk_mul_f32 v[132:133], v[14:15], v[134:135] op_sel_hi:[0,1]
	ds_read2_b32 v[134:135], v125 offset0:40 offset1:42
	ds_write2_b32 v125, v132, v133 offset0:32 offset1:34
	s_waitcnt lgkmcnt(3)
	v_pk_mul_f32 v[132:133], v[14:15], v[136:137] op_sel_hi:[0,1]
	ds_read2_b32 v[136:137], v125 offset0:44 offset1:46
	ds_write2_b32 v125, v132, v133 offset0:36 offset1:38
	s_waitcnt lgkmcnt(3)
	v_pk_mul_f32 v[132:133], v[14:15], v[134:135] op_sel_hi:[0,1]
	ds_read2_b32 v[134:135], v125 offset0:48 offset1:50
	ds_write2_b32 v125, v132, v133 offset0:40 offset1:42
	s_waitcnt lgkmcnt(3)
	v_pk_mul_f32 v[132:133], v[14:15], v[136:137] op_sel_hi:[0,1]
	ds_read2_b32 v[136:137], v125 offset0:52 offset1:54
	ds_write2_b32 v125, v132, v133 offset0:44 offset1:46
	s_waitcnt lgkmcnt(3)
	v_pk_mul_f32 v[132:133], v[14:15], v[134:135] op_sel_hi:[0,1]
	ds_read2_b32 v[134:135], v125 offset0:56 offset1:58
	ds_write2_b32 v125, v132, v133 offset0:48 offset1:50
	s_waitcnt lgkmcnt(3)
	v_pk_mul_f32 v[132:133], v[14:15], v[136:137] op_sel_hi:[0,1]
	ds_read2_b32 v[136:137], v125 offset0:60 offset1:62
	ds_write2_b32 v125, v132, v133 offset0:52 offset1:54
	s_waitcnt lgkmcnt(3)
	v_pk_mul_f32 v[132:133], v[14:15], v[134:135] op_sel_hi:[0,1]
	ds_read2_b32 v[134:135], v125 offset0:64 offset1:66
	ds_write2_b32 v125, v132, v133 offset0:56 offset1:58
	s_waitcnt lgkmcnt(3)
	v_pk_mul_f32 v[132:133], v[14:15], v[136:137] op_sel_hi:[0,1]
	ds_read2_b32 v[136:137], v125 offset0:68 offset1:70
	ds_write2_b32 v125, v132, v133 offset0:60 offset1:62
	s_waitcnt lgkmcnt(3)
	v_pk_mul_f32 v[132:133], v[14:15], v[134:135] op_sel_hi:[0,1]
	ds_read2_b32 v[134:135], v125 offset0:72 offset1:74
	ds_write2_b32 v125, v132, v133 offset0:64 offset1:66
	s_waitcnt lgkmcnt(3)
	v_pk_mul_f32 v[132:133], v[14:15], v[136:137] op_sel_hi:[0,1]
	ds_read2_b32 v[136:137], v125 offset0:76 offset1:78
	ds_write2_b32 v125, v132, v133 offset0:68 offset1:70
	s_waitcnt lgkmcnt(3)
	v_pk_mul_f32 v[132:133], v[14:15], v[134:135] op_sel_hi:[0,1]
	ds_read2_b32 v[134:135], v125 offset0:80 offset1:82
	ds_write2_b32 v125, v132, v133 offset0:72 offset1:74
	s_waitcnt lgkmcnt(3)
	v_pk_mul_f32 v[132:133], v[14:15], v[136:137] op_sel_hi:[0,1]
	ds_read2_b32 v[136:137], v125 offset0:84 offset1:86
	ds_write2_b32 v125, v132, v133 offset0:76 offset1:78
	s_waitcnt lgkmcnt(3)
	v_pk_mul_f32 v[132:133], v[14:15], v[134:135] op_sel_hi:[0,1]
	ds_read2_b32 v[134:135], v125 offset0:88 offset1:90
	ds_write2_b32 v125, v132, v133 offset0:80 offset1:82
	s_waitcnt lgkmcnt(3)
	v_pk_mul_f32 v[132:133], v[14:15], v[136:137] op_sel_hi:[0,1]
	ds_read2_b32 v[136:137], v125 offset0:92 offset1:94
	ds_write2_b32 v125, v132, v133 offset0:84 offset1:86
	s_waitcnt lgkmcnt(3)
	v_pk_mul_f32 v[132:133], v[14:15], v[134:135] op_sel_hi:[0,1]
	ds_read2_b32 v[134:135], v125 offset0:96 offset1:98
	ds_write2_b32 v125, v132, v133 offset0:88 offset1:90
	s_waitcnt lgkmcnt(3)
	v_pk_mul_f32 v[132:133], v[14:15], v[136:137] op_sel_hi:[0,1]
	ds_read2_b32 v[136:137], v125 offset0:100 offset1:102
	ds_write2_b32 v125, v132, v133 offset0:92 offset1:94
	s_waitcnt lgkmcnt(3)
	v_pk_mul_f32 v[132:133], v[14:15], v[134:135] op_sel_hi:[0,1]
	ds_read2_b32 v[134:135], v125 offset0:104 offset1:106
	ds_write2_b32 v125, v132, v133 offset0:96 offset1:98
	s_waitcnt lgkmcnt(3)
	v_pk_mul_f32 v[132:133], v[14:15], v[136:137] op_sel_hi:[0,1]
	ds_read2_b32 v[136:137], v125 offset0:108 offset1:110
	ds_write2_b32 v125, v132, v133 offset0:100 offset1:102
	s_waitcnt lgkmcnt(3)
	v_pk_mul_f32 v[132:133], v[14:15], v[134:135] op_sel_hi:[0,1]
	ds_read2_b32 v[134:135], v125 offset0:112 offset1:114
	ds_write2_b32 v125, v132, v133 offset0:104 offset1:106
	s_waitcnt lgkmcnt(3)
	v_pk_mul_f32 v[132:133], v[14:15], v[136:137] op_sel_hi:[0,1]
	ds_write2_b32 v125, v132, v133 offset0:108 offset1:110
	ds_read2_b32 v[132:133], v125 offset0:116 offset1:118
	s_waitcnt lgkmcnt(3)
	v_pk_mul_f32 v[134:135], v[14:15], v[134:135] op_sel_hi:[0,1]
	ds_read2_b32 v[136:137], v125 offset0:120 offset1:122
	ds_write2_b32 v125, v134, v135 offset0:112 offset1:114
	ds_read2_b32 v[134:135], v125 offset0:124 offset1:126
	s_waitcnt lgkmcnt(3)
	v_pk_mul_f32 v[132:133], v[14:15], v[132:133] op_sel_hi:[0,1]
	ds_write2_b32 v125, v132, v133 offset0:116 offset1:118
	s_waitcnt lgkmcnt(3)
	v_pk_mul_f32 v[132:133], v[14:15], v[136:137] op_sel_hi:[0,1]
	ds_write2_b32 v125, v132, v133 offset0:120 offset1:122
	s_waitcnt lgkmcnt(2)
	v_pk_mul_f32 v[14:15], v[14:15], v[134:135] op_sel_hi:[0,1]
	ds_write2_b32 v125, v14, v15 offset0:124 offset1:126

; DI float fast_exp2(float x) { return __builtin_amdgcn_exp2f(x); }
; DI float xhalf_max(float v) { const auto rr = __builtin_amdgcn_permlane32_swap(__float_as_uint(v), __float_as_uint(v), false, false); return fmaxf(__uint_as_float(rr[0]), __uint_as_float(rr[1])); }
; DI float soft_update(Soft& f, f32x16& x0, f32x16& x1, bool hasO) {
;     float ma = fmaxf(fmaxf(x0[0], x1[0]), x0[1]), mb = fmaxf(fmaxf(x1[1], x0[2]), x1[2]);
; #pragma unroll
;     for (int r = 3; r < 15; r += 2) { ma = fmaxf(fmaxf(ma, x0[r]), x1[r]); mb = fmaxf(fmaxf(mb, x0[r + 1]), x1[r + 1]); }
;     ma = fmaxf(fmaxf(ma, x0[15]), x1[15]);
;     float mx = xhalf_max(fmaxf(ma, mb));
;     const bool valid = mx > -1e20f;
;     const bool need = valid && (mx > 8.f || !f.seen);
;     float dmove = 0.f;
;     if (__builtin_amdgcn_ballot_w64(need)) {
;         const float delta = need ? fmaxf(mx, -60.f) : 0.f; const float sc = fast_exp2(-delta);
;         dmove = delta;
;         f.mref += delta; f.l *= sc;
;         if (hasO) {
; #pragma unroll
;             for (int r = 0; r < 16; ++r) { f.o0[r] *= sc; f.o1[r] *= sc; } }
; #pragma unroll
;         for (int r = 0; r < 16; ++r) { x0[r] -= delta; x1[r] -= delta; }
;     }
.LBB0_1001:
	s_nop 10
	v_max_f32_e32 v1, v80, v80
	v_max_f32_e32 v14, v96, v96
	v_max_f32_e32 v1, v14, v1
	v_max3_f32 v14, v81, v98, v82
	v_max3_f32 v1, v1, v97, v99
	v_max3_f32 v14, v14, v100, v84
	v_max3_f32 v1, v1, v83, v101
	v_max3_f32 v14, v14, v102, v86
	v_max3_f32 v1, v1, v85, v103
	v_max3_f32 v14, v14, v104, v88
	v_max3_f32 v1, v1, v87, v105
	v_max3_f32 v14, v14, v106, v90
	v_max3_f32 v1, v1, v89, v107
	v_max3_f32 v14, v14, v108, v92
	v_max3_f32 v1, v1, v91, v109
	v_max3_f32 v14, v14, v110, v94
	v_max3_f32 v1, v1, v93, v111
	v_max3_f32 v1, v1, v95, v14
	v_mov_b32_e32 v14, v1
	s_nop 1
	v_permlane32_swap_b32_e32 v1, v14
	v_max_f32_e32 v14, v14, v14
	v_max_f32_e32 v1, v1, v1
	v_max_f32_e32 v1, v1, v14
	v_cmp_lt_f32_e64 s[6:7], s70, v1
	v_cmp_lt_f32_e64 s[8:9], s84, v1
	s_orn2_b64 s[8:9], s[8:9], s[4:5]
	s_and_b64 s[8:9], s[8:9], s[6:7]
	s_cbranch_scc0 .LBB0_1007
	v_max_f32_e32 v1, v1, v1
	v_max_f32_e32 v1, 0xc2700000, v1
	v_cndmask_b32_e64 v14, 0, v1, s[8:9]
	v_exp_f32_e64 v174, -v14
	v_add_f32_e32 v167, v167, v14
	v_pk_add_f32 v[96:97], v[96:97], v[14:15] op_sel_hi:[1,0] neg_lo:[0,1] neg_hi:[0,1]
	v_pk_add_f32 v[80:81], v[80:81], v[14:15] op_sel_hi:[1,0] neg_lo:[0,1] neg_hi:[0,1]
	v_mul_f32_e32 v211, v211, v174
	v_pk_mul_f32 v[78:79], v[78:79], v[174:175] op_sel_hi:[1,0]
	v_pk_mul_f32 v[76:77], v[76:77], v[174:175] op_sel_hi:[1,0]
	v_pk_mul_f32 v[74:75], v[74:75], v[174:175] op_sel_hi:[1,0]
	v_pk_mul_f32 v[72:73], v[72:73], v[174:175] op_sel_hi:[1,0]
	v_pk_mul_f32 v[70:71], v[70:71], v[174:175] op_sel_hi:[1,0]
	v_pk_mul_f32 v[68:69], v[68:69], v[174:175] op_sel_hi:[1,0]
	v_pk_mul_f32 v[66:67], v[66:67], v[174:175] op_sel_hi:[1,0]
	v_pk_mul_f32 v[64:65], v[64:65], v[174:175] op_sel_hi:[1,0]
	v_pk_mul_f32 v[62:63], v[62:63], v[174:175] op_sel_hi:[1,0]
	v_pk_mul_f32 v[60:61], v[60:61], v[174:175] op_sel_hi:[1,0]
	v_pk_mul_f32 v[58:59], v[58:59], v[174:175] op_sel_hi:[1,0]
	v_pk_mul_f32 v[56:57], v[56:57], v[174:175] op_sel_hi:[1,0]
	v_pk_mul_f32 v[54:55], v[54:55], v[174:175] op_sel_hi:[1,0]
	v_pk_mul_f32 v[52:53], v[52:53], v[174:175] op_sel_hi:[1,0]
	v_pk_mul_f32 v[50:51], v[50:51], v[174:175] op_sel_hi:[1,0]
	v_pk_mul_f32 v[48:49], v[48:49], v[174:175] op_sel_hi:[1,0]
	v_pk_add_f32 v[98:99], v[98:99], v[14:15] op_sel_hi:[1,0] neg_lo:[0,1] neg_hi:[0,1]
	v_pk_add_f32 v[82:83], v[82:83], v[14:15] op_sel_hi:[1,0] neg_lo:[0,1] neg_hi:[0,1]
	v_pk_add_f32 v[100:101], v[100:101], v[14:15] op_sel_hi:[1,0] neg_lo:[0,1] neg_hi:[0,1]
	v_pk_add_f32 v[84:85], v[84:85], v[14:15] op_sel_hi:[1,0] neg_lo:[0,1] neg_hi:[0,1]
	v_pk_add_f32 v[102:103], v[102:103], v[14:15] op_sel_hi:[1,0] neg_lo:[0,1] neg_hi:[0,1]
	v_pk_add_f32 v[86:87], v[86:87], v[14:15] op_sel_hi:[1,0] neg_lo:[0,1] neg_hi:[0,1]
	v_pk_add_f32 v[104:105], v[104:105], v[14:15] op_sel_hi:[1,0] neg_lo:[0,1] neg_hi:[0,1]
	v_pk_add_f32 v[88:89], v[88:89], v[14:15] op_sel_hi:[1,0] neg_lo:[0,1] neg_hi:[0,1]
	v_pk_add_f32 v[106:107], v[106:107], v[14:15] op_sel_hi:[1,0] neg_lo:[0,1] neg_hi:[0,1]
	v_pk_add_f32 v[90:91], v[90:91], v[14:15] op_sel_hi:[1,0] neg_lo:[0,1] neg_hi:[0,1]
	v_pk_add_f32 v[108:109], v[108:109], v[14:15] op_sel_hi:[1,0] neg_lo:[0,1] neg_hi:[0,1]
	v_pk_add_f32 v[92:93], v[92:93], v[14:15] op_sel_hi:[1,0] neg_lo:[0,1] neg_hi:[0,1]
	v_pk_add_f32 v[110:111], v[110:111], v[14:15] op_sel_hi:[1,0] neg_lo:[0,1] neg_hi:[0,1]
	v_pk_add_f32 v[94:95], v[94:95], v[14:15] op_sel_hi:[1,0] neg_lo:[0,1] neg_hi:[0,1]

; DI float fast_exp2(float x) { return __builtin_amdgcn_exp2f(x); }
; DI float xhalf_max(float v) { const auto rr = __builtin_amdgcn_permlane32_swap(__float_as_uint(v), __float_as_uint(v), false, false); return fmaxf(__uint_as_float(rr[0]), __uint_as_float(rr[1])); }
; DI float soft_update(Soft& f, f32x16& x0, f32x16& x1, bool hasO) {
;     float ma = fmaxf(fmaxf(x0[0], x1[0]), x0[1]), mb = fmaxf(fmaxf(x1[1], x0[2]), x1[2]);
; #pragma unroll
;     for (int r = 3; r < 15; r += 2) { ma = fmaxf(fmaxf(ma, x0[r]), x1[r]); mb = fmaxf(fmaxf(mb, x0[r + 1]), x1[r + 1]); }
;     ma = fmaxf(fmaxf(ma, x0[15]), x1[15]);
;     float mx = xhalf_max(fmaxf(ma, mb));
;     const bool valid = mx > -1e20f;
;     const bool need = valid && (mx > 8.f || !f.seen);
;     float dmove = 0.f;
;     if (__builtin_amdgcn_ballot_w64(need)) {
;         const float delta = need ? fmaxf(mx, -60.f) : 0.f; const float sc = fast_exp2(-delta);
;         dmove = delta;
;         f.mref += delta; f.l *= sc;
;         if (hasO) {
; #pragma unroll
;             for (int r = 0; r < 16; ++r) { f.o0[r] *= sc; f.o1[r] *= sc; } }
; #pragma unroll
;         for (int r = 0; r < 16; ++r) { x0[r] -= delta; x1[r] -= delta; }
;     }
.LBB0_1024:
	s_nop 10
	v_max_f32_e32 v14, v112, v112
	v_max_f32_e32 v15, v128, v128
	v_max_f32_e32 v14, v15, v14
	v_max3_f32 v15, v113, v130, v114
	v_max3_f32 v14, v14, v129, v131
	v_max3_f32 v15, v15, v132, v116
	v_max3_f32 v14, v14, v115, v133
	v_max3_f32 v15, v15, v134, v118
	v_max3_f32 v14, v14, v117, v135
	v_max3_f32 v15, v15, v136, v120
	v_max3_f32 v14, v14, v119, v137
	v_max3_f32 v15, v15, v138, v122
	v_max3_f32 v14, v14, v121, v139
	v_max3_f32 v15, v15, v140, v124
	v_max3_f32 v14, v14, v123, v141
	v_max3_f32 v15, v15, v142, v126
	v_max3_f32 v14, v14, v125, v143
	v_max3_f32 v14, v14, v127, v15
	v_mov_b32_e32 v15, v14
	s_nop 1
	v_permlane32_swap_b32_e32 v14, v15
	v_max_f32_e32 v15, v15, v15
	v_max_f32_e32 v14, v14, v14
	v_max_f32_e32 v14, v14, v15
	v_cmp_lt_f32_e64 s[6:7], s70, v14
	v_cmp_lt_f32_e64 s[8:9], s84, v14
	s_orn2_b64 s[8:9], s[8:9], s[4:5]
	s_and_b64 s[8:9], s[8:9], s[6:7]
	s_cbranch_scc0 .LBB0_1030
	v_max_f32_e32 v14, v14, v14
	v_max_f32_e32 v14, 0xc2700000, v14
	v_cndmask_b32_e64 v14, 0, v14, s[8:9]
	v_exp_f32_e64 v250, -v14
	v_add_f32_e32 v1, v1, v14
	v_pk_add_f32 v[128:129], v[128:129], v[14:15] op_sel_hi:[1,0] neg_lo:[0,1] neg_hi:[0,1]
	v_pk_add_f32 v[112:113], v[112:113], v[14:15] op_sel_hi:[1,0] neg_lo:[0,1] neg_hi:[0,1]
	v_mul_f32_e32 v210, v210, v250
	v_pk_mul_f32 v[110:111], v[110:111], v[250:251] op_sel_hi:[1,0]
	v_pk_mul_f32 v[108:109], v[108:109], v[250:251] op_sel_hi:[1,0]
	v_pk_mul_f32 v[106:107], v[106:107], v[250:251] op_sel_hi:[1,0]
	v_pk_mul_f32 v[104:105], v[104:105], v[250:251] op_sel_hi:[1,0]
	v_pk_mul_f32 v[102:103], v[102:103], v[250:251] op_sel_hi:[1,0]
	v_pk_mul_f32 v[100:101], v[100:101], v[250:251] op_sel_hi:[1,0]
	v_pk_mul_f32 v[98:99], v[98:99], v[250:251] op_sel_hi:[1,0]
	v_pk_mul_f32 v[96:97], v[96:97], v[250:251] op_sel_hi:[1,0]
	v_pk_mul_f32 v[94:95], v[94:95], v[250:251] op_sel_hi:[1,0]
	v_pk_mul_f32 v[92:93], v[92:93], v[250:251] op_sel_hi:[1,0]
	v_pk_mul_f32 v[90:91], v[90:91], v[250:251] op_sel_hi:[1,0]
	v_pk_mul_f32 v[88:89], v[88:89], v[250:251] op_sel_hi:[1,0]
	v_pk_mul_f32 v[86:87], v[86:87], v[250:251] op_sel_hi:[1,0]
	v_pk_mul_f32 v[84:85], v[84:85], v[250:251] op_sel_hi:[1,0]
	v_pk_mul_f32 v[82:83], v[82:83], v[250:251] op_sel_hi:[1,0]
	v_pk_mul_f32 v[80:81], v[80:81], v[250:251] op_sel_hi:[1,0]
	v_pk_add_f32 v[130:131], v[130:131], v[14:15] op_sel_hi:[1,0] neg_lo:[0,1] neg_hi:[0,1]
	v_pk_add_f32 v[114:115], v[114:115], v[14:15] op_sel_hi:[1,0] neg_lo:[0,1] neg_hi:[0,1]
	v_pk_add_f32 v[132:133], v[132:133], v[14:15] op_sel_hi:[1,0] neg_lo:[0,1] neg_hi:[0,1]
	v_pk_add_f32 v[116:117], v[116:117], v[14:15] op_sel_hi:[1,0] neg_lo:[0,1] neg_hi:[0,1]
	v_pk_add_f32 v[134:135], v[134:135], v[14:15] op_sel_hi:[1,0] neg_lo:[0,1] neg_hi:[0,1]
	v_pk_add_f32 v[118:119], v[118:119], v[14:15] op_sel_hi:[1,0] neg_lo:[0,1] neg_hi:[0,1]
	v_pk_add_f32 v[136:137], v[136:137], v[14:15] op_sel_hi:[1,0] neg_lo:[0,1] neg_hi:[0,1]
	v_pk_add_f32 v[120:121], v[120:121], v[14:15] op_sel_hi:[1,0] neg_lo:[0,1] neg_hi:[0,1]
	v_pk_add_f32 v[138:139], v[138:139], v[14:15] op_sel_hi:[1,0] neg_lo:[0,1] neg_hi:[0,1]
	v_pk_add_f32 v[122:123], v[122:123], v[14:15] op_sel_hi:[1,0] neg_lo:[0,1] neg_hi:[0,1]
	v_pk_add_f32 v[140:141], v[140:141], v[14:15] op_sel_hi:[1,0] neg_lo:[0,1] neg_hi:[0,1]
	v_pk_add_f32 v[124:125], v[124:125], v[14:15] op_sel_hi:[1,0] neg_lo:[0,1] neg_hi:[0,1]
	v_pk_add_f32 v[142:143], v[142:143], v[14:15] op_sel_hi:[1,0] neg_lo:[0,1] neg_hi:[0,1]
	v_pk_add_f32 v[126:127], v[126:127], v[14:15] op_sel_hi:[1,0] neg_lo:[0,1] neg_hi:[0,1]

; DI float fast_exp2(float x) { return __builtin_amdgcn_exp2f(x); }
; #define MFMA32(a, b, c) __builtin_amdgcn_mfma_f32_32x32x16_bf16((a), (b), (c), 0, 0, 0)
; DI int crow(int r, int hi) { return (r & 3) + 8 * (r >> 2) + 4 * hi; }
; DI float xhalf_max(float v) { const auto rr = __builtin_amdgcn_permlane32_swap(__float_as_uint(v), __float_as_uint(v), false, false); return fmaxf(__uint_as_float(rr[0]), __uint_as_float(rr[1])); }
; DI int ccol(int r) { return (r & 3) + 8 * (r >> 2); }
; #define DIL_LOAD(slot, s_) do { const int ip_ = i0 - 32 * (s_) >= ipf ? i0 - 32 * (s_) : ipf; const size_t to_ = (size_t)((pr + ip_) >> 5) * 2048; load_kf(Kq[slot], kpl + to_, r32, hi); load_vf(Vq[slot], vpl + to_, r32, hi); } while (0)
; DI void frag_scores(f32x16& x0, const KFrag& K0, const bf16x8 (&qf)[4], float sk, float aref, int p0, bool needmask, int lo, int hip, int hi) {
;     const float B = fmaf(sk, (float)(p0 + 4 * hi), -aref);
; #pragma unroll
;     for (int r = 0; r < 16; ++r) x0[r] = fmaf(sk, (float)ccol(r), B);
; #pragma unroll
;     for (int d0 = 0; d0 < 4; ++d0) x0 = MFMA32(K0.k[d0], qf[d0], x0);
;     if (needmask) {
; #pragma unroll
;         for (int r = 0; r < 16; ++r) { const int pos = p0 + crow(r, hi); if (pos < lo || pos > hip) x0[r] = -1e30f; }
;     }
; }
; DI void soft_update1(Soft& f, f32x16& x0) {
;     float mx = x0[0];
; #pragma unroll
;     for (int r = 1; r < 16; ++r) mx = fmaxf(mx, x0[r]);
;     mx = xhalf_max(mx);
;     const bool valid = mx > -1e20f;
;     const bool need = valid && (mx > 8.f || !f.seen);
;     if (__builtin_amdgcn_ballot_w64(need)) {
;         const float delta = need ? fmaxf(mx, -60.f) : 0.f; const float sc = fast_exp2(-delta);
;         f.mref += delta; f.l *= sc;
; #pragma unroll
;         for (int r = 0; r < 16; ++r) { f.o0[r] *= sc; f.o1[r] *= sc; x0[r] -= delta; }
;     }
; DI void dil_unit(const bf16* PR, const bf16* VT, bf16* Y, LAS unsigned char* lds, int b, int hh, int tb) {
;     ...
;             DIL_LOAD(0, 0); DIL_LOAD(1, 1);
; #pragma unroll
;             for (int s = 0; s < 5; ++s) {
;                 if (s + 2 < 5) DIL_LOAD((s + 2) % 3, s + 2);
.LBB0_1046:
	s_add_i32 s72, s67, 0xffffffa0
	s_max_i32 s3, s72, s68
	s_add_i32 s3, s3, s69
	s_ashr_i32 s4, s3, 5
	s_ashr_i32 s5, s4, 31
	s_lshl_b64 s[4:5], s[4:5], 12
	v_lshl_add_u64 v[34:35], v[172:173], 0, s[4:5]
	global_load_dwordx4 v[142:145], v[34:35], off
	global_load_dwordx4 v[138:141], v[34:35], off offset:1024
	global_load_dwordx4 v[134:137], v[34:35], off offset:2048
	global_load_dwordx4 v[130:133], v[34:35], off offset:3072
	v_lshl_add_u64 v[34:35], v[170:171], 0, s[4:5]
	global_load_dwordx2 v[126:127], v[34:35], off
	global_load_dwordx2 v[128:129], v[34:35], off offset:512
	global_load_dwordx2 v[122:123], v[34:35], off offset:1024
	global_load_dwordx2 v[124:125], v[34:35], off offset:1536
	global_load_dwordx2 v[118:119], v[34:35], off offset:2048
	global_load_dwordx2 v[120:121], v[34:35], off offset:2560
	global_load_dwordx2 v[110:111], v[34:35], off offset:3072
	global_load_dwordx2 v[112:113], v[34:35], off offset:3584
	s_cmp_lt_i32 s2, s68
	s_cbranch_scc1 .LBB0_1054
	v_subrev_u32_e32 v34, 32, v181
	v_cvt_f32_u32_e32 v34, v34
	v_add_f32_e32 v35, v182, v183
	s_mov_b64 s[4:5], 0
	v_fma_f32 v48, v168, v34, -v35
	v_fma_f32 v34, 0, v168, v48
	v_add_f32_e32 v35, v168, v48
	v_pk_fma_f32 v[36:37], v[168:169], s[82:83], v[48:49] op_sel_hi:[1,1,0]
	v_pk_fma_f32 v[38:39], v[168:169], s[84:85], v[48:49] op_sel_hi:[1,1,0]
	v_pk_fma_f32 v[40:41], v[168:169], s[86:87], v[48:49] op_sel_hi:[1,1,0]
	v_pk_fma_f32 v[42:43], v[168:169], s[80:81], v[48:49] op_sel_hi:[1,1,0]
	v_pk_fma_f32 v[44:45], v[168:169], s[88:89], v[48:49] op_sel_hi:[1,1,0]
	v_pk_fma_f32 v[46:47], v[168:169], s[90:91], v[48:49] op_sel_hi:[1,1,0]
	v_pk_fma_f32 v[48:49], v[168:169], s[92:93], v[48:49] op_sel_hi:[1,1,0]
	s_waitcnt vmcnt(35)
	s_nop 0
	v_mfma_f32_32x32x16_bf16 v[34:49], v[158:161], v[50:53], v[34:49]
	s_waitcnt vmcnt(34)
	v_mfma_f32_32x32x16_bf16 v[34:49], v[154:157], v[54:57], v[34:49]
	s_waitcnt vmcnt(33)
	v_mfma_f32_32x32x16_bf16 v[34:49], v[150:153], v[58:61], v[34:49]
	s_waitcnt vmcnt(32)
	v_mfma_f32_32x32x16_bf16 v[34:49], v[146:149], v[62:65], v[34:49]
	s_nop 11
	v_max_f32_e32 v146, v35, v35
	v_max_f32_e32 v147, v34, v34
	v_max_f32_e32 v146, v147, v146
	v_max3_f32 v146, v146, v36, v37
	v_max3_f32 v146, v146, v38, v39
	v_max3_f32 v146, v146, v40, v41
	v_max3_f32 v146, v146, v42, v43
	v_max3_f32 v146, v146, v44, v45
	v_max3_f32 v146, v146, v46, v47
	v_max3_f32 v146, v146, v48, v49
	v_mov_b32_e32 v147, v146
	s_nop 1
	v_permlane32_swap_b32_e32 v146, v147
	v_max_f32_e32 v147, v147, v147
	v_max_f32_e32 v146, v146, v146
	v_max_f32_e32 v146, v146, v147
	v_cmp_lt_f32_e64 s[40:41], s70, v146
	v_cmp_lt_f32_e64 s[4:5], s84, v146
	s_orn2_b64 s[4:5], s[4:5], s[38:39]
	s_and_b64 s[4:5], s[4:5], s[40:41]
	s_cbranch_scc0 .LBB0_1053
	v_max_f32_e32 v146, v146, v146
	v_max_f32_e32 v146, 0xc2700000, v146
	v_cndmask_b32_e64 v146, 0, v146, s[4:5]
	v_exp_f32_e64 v148, -v146
	v_add_f32_e32 v183, v183, v146
	v_pk_add_f32 v[34:35], v[34:35], v[146:147] op_sel_hi:[1,0] neg_lo:[0,1] neg_hi:[0,1]
	v_pk_add_f32 v[36:37], v[36:37], v[146:147] op_sel_hi:[1,0] neg_lo:[0,1] neg_hi:[0,1]
	v_mul_f32_e32 v1, v1, v148
	v_pk_add_f32 v[38:39], v[38:39], v[146:147] op_sel_hi:[1,0] neg_lo:[0,1] neg_hi:[0,1]
	v_pk_add_f32 v[40:41], v[40:41], v[146:147] op_sel_hi:[1,0] neg_lo:[0,1] neg_hi:[0,1]
	v_pk_add_f32 v[42:43], v[42:43], v[146:147] op_sel_hi:[1,0] neg_lo:[0,1] neg_hi:[0,1]
	v_pk_add_f32 v[44:45], v[44:45], v[146:147] op_sel_hi:[1,0] neg_lo:[0,1] neg_hi:[0,1]
	v_pk_add_f32 v[46:47], v[46:47], v[146:147] op_sel_hi:[1,0] neg_lo:[0,1] neg_hi:[0,1]
	v_pk_mul_f32 v[32:33], v[32:33], v[148:149] op_sel_hi:[1,0]
	v_pk_mul_f32 v[30:31], v[30:31], v[148:149] op_sel_hi:[1,0]
	v_pk_mul_f32 v[28:29], v[28:29], v[148:149] op_sel_hi:[1,0]
	v_pk_mul_f32 v[26:27], v[26:27], v[148:149] op_sel_hi:[1,0]
	v_pk_mul_f32 v[24:25], v[24:25], v[148:149] op_sel_hi:[1,0]
	v_pk_mul_f32 v[22:23], v[22:23], v[148:149] op_sel_hi:[1,0]
	v_pk_mul_f32 v[20:21], v[20:21], v[148:149] op_sel_hi:[1,0]
	v_pk_mul_f32 v[18:19], v[18:19], v[148:149] op_sel_hi:[1,0]
	v_pk_mul_f32 v[16:17], v[16:17], v[148:149] op_sel_hi:[1,0]
	v_pk_mul_f32 v[14:15], v[14:15], v[148:149] op_sel_hi:[1,0]
	v_pk_mul_f32 v[12:13], v[12:13], v[148:149] op_sel_hi:[1,0]
	v_pk_mul_f32 v[10:11], v[10:11], v[148:149] op_sel_hi:[1,0]
	v_pk_mul_f32 v[8:9], v[8:9], v[148:149] op_sel_hi:[1,0]
	v_pk_mul_f32 v[6:7], v[6:7], v[148:149] op_sel_hi:[1,0]
	v_pk_mul_f32 v[4:5], v[4:5], v[148:149] op_sel_hi:[1,0]
	v_pk_mul_f32 v[2:3], v[2:3], v[148:149] op_sel_hi:[1,0]
	v_pk_add_f32 v[48:49], v[48:49], v[146:147] op_sel_hi:[1,0] neg_lo:[0,1] neg_hi:[0,1]

; DI float fast_exp2(float x) { return __builtin_amdgcn_exp2f(x); }
; #define MFMA32(a, b, c) __builtin_amdgcn_mfma_f32_32x32x16_bf16((a), (b), (c), 0, 0, 0)
; DI int crow(int r, int hi) { return (r & 3) + 8 * (r >> 2) + 4 * hi; }
; DI float xhalf_max(float v) { const auto rr = __builtin_amdgcn_permlane32_swap(__float_as_uint(v), __float_as_uint(v), false, false); return fmaxf(__uint_as_float(rr[0]), __uint_as_float(rr[1])); }
; DI int ccol(int r) { return (r & 3) + 8 * (r >> 2); }
; #define DIL_LOAD(slot, s_) do { const int ip_ = i0 - 32 * (s_) >= ipf ? i0 - 32 * (s_) : ipf; const size_t to_ = (size_t)((pr + ip_) >> 5) * 2048; load_kf(Kq[slot], kpl + to_, r32, hi); load_vf(Vq[slot], vpl + to_, r32, hi); } while (0)
; DI void frag_scores(f32x16& x0, const KFrag& K0, const bf16x8 (&qf)[4], float sk, float aref, int p0, bool needmask, int lo, int hip, int hi) {
;     const float B = fmaf(sk, (float)(p0 + 4 * hi), -aref);
; #pragma unroll
;     for (int r = 0; r < 16; ++r) x0[r] = fmaf(sk, (float)ccol(r), B);
; #pragma unroll
;     for (int d0 = 0; d0 < 4; ++d0) x0 = MFMA32(K0.k[d0], qf[d0], x0);
;     if (needmask) {
; #pragma unroll
;         for (int r = 0; r < 16; ++r) { const int pos = p0 + crow(r, hi); if (pos < lo || pos > hip) x0[r] = -1e30f; }
;     }
; }
; DI void soft_update1(Soft& f, f32x16& x0) {
;     float mx = x0[0];
; #pragma unroll
;     for (int r = 1; r < 16; ++r) mx = fmaxf(mx, x0[r]);
;     mx = xhalf_max(mx);
;     const bool valid = mx > -1e20f;
;     const bool need = valid && (mx > 8.f || !f.seen);
;     if (__builtin_amdgcn_ballot_w64(need)) {
;         const float delta = need ? fmaxf(mx, -60.f) : 0.f; const float sc = fast_exp2(-delta);
;         f.mref += delta; f.l *= sc;
; #pragma unroll
;         for (int r = 0; r < 16; ++r) { f.o0[r] *= sc; f.o1[r] *= sc; x0[r] -= delta; }
;     }
; DI void dil_unit(const bf16* PR, const bf16* VT, bf16* Y, LAS unsigned char* lds, int b, int hh, int tb) {
;     ...
;             DIL_LOAD(0, 0); DIL_LOAD(1, 1);
; #pragma unroll
;             for (int s = 0; s < 5; ++s) {
;                 if (s + 2 < 5) DIL_LOAD((s + 2) % 3, s + 2);
.LBB0_1054:
	s_add_i32 s2, s67, 0xffffff80
	s_max_i32 s2, s2, s68
	s_add_i32 s2, s2, s69
	s_ashr_i32 s2, s2, 5
	s_ashr_i32 s3, s2, 31
	s_lshl_b64 s[2:3], s[2:3], 12
	v_lshl_add_u64 v[34:35], v[172:173], 0, s[2:3]
	global_load_dwordx4 v[146:149], v[34:35], off
	global_load_dwordx4 v[150:153], v[34:35], off offset:1024
	global_load_dwordx4 v[154:157], v[34:35], off offset:2048
	global_load_dwordx4 v[158:161], v[34:35], off offset:3072
	v_lshl_add_u64 v[34:35], v[170:171], 0, s[2:3]
	global_load_dwordx2 v[114:115], v[34:35], off
	global_load_dwordx2 v[116:117], v[34:35], off offset:512
	global_load_dwordx2 v[106:107], v[34:35], off offset:1024
	global_load_dwordx2 v[108:109], v[34:35], off offset:1536
	global_load_dwordx2 v[90:91], v[34:35], off offset:2048
	global_load_dwordx2 v[92:93], v[34:35], off offset:2560
	global_load_dwordx2 v[82:83], v[34:35], off offset:3072
	global_load_dwordx2 v[84:85], v[34:35], off offset:3584
	s_cmp_lt_i32 s71, s68
	s_cbranch_scc1 .LBB0_1063
	v_subrev_u32_e32 v34, 64, v181
	v_cvt_f32_u32_e32 v34, v34
	v_add_f32_e32 v35, v182, v183
	s_mov_b64 s[4:5], 0
	v_fma_f32 v48, v168, v34, -v35
	v_fma_f32 v34, 0, v168, v48
	v_add_f32_e32 v35, v168, v48
	v_pk_fma_f32 v[36:37], v[168:169], s[82:83], v[48:49] op_sel_hi:[1,1,0]
	v_pk_fma_f32 v[38:39], v[168:169], s[84:85], v[48:49] op_sel_hi:[1,1,0]
	v_pk_fma_f32 v[40:41], v[168:169], s[86:87], v[48:49] op_sel_hi:[1,1,0]
	v_pk_fma_f32 v[42:43], v[168:169], s[80:81], v[48:49] op_sel_hi:[1,1,0]
	v_pk_fma_f32 v[44:45], v[168:169], s[88:89], v[48:49] op_sel_hi:[1,1,0]
	v_pk_fma_f32 v[46:47], v[168:169], s[90:91], v[48:49] op_sel_hi:[1,1,0]
	v_pk_fma_f32 v[48:49], v[168:169], s[92:93], v[48:49] op_sel_hi:[1,1,0]
	s_waitcnt vmcnt(35)
	s_nop 0
	v_mfma_f32_32x32x16_bf16 v[34:49], v[102:105], v[50:53], v[34:49]
	s_waitcnt vmcnt(34)
	v_mfma_f32_32x32x16_bf16 v[34:49], v[98:101], v[54:57], v[34:49]
	s_waitcnt vmcnt(33)
	v_mfma_f32_32x32x16_bf16 v[34:49], v[94:97], v[58:61], v[34:49]
	s_waitcnt vmcnt(32)
	v_mfma_f32_32x32x16_bf16 v[34:49], v[86:89], v[62:65], v[34:49]
	s_nop 11
	v_max_f32_e32 v86, v35, v35
	v_max_f32_e32 v87, v34, v34
	v_max_f32_e32 v86, v87, v86
	v_max3_f32 v86, v86, v36, v37
	v_max3_f32 v86, v86, v38, v39
	v_max3_f32 v86, v86, v40, v41
	v_max3_f32 v86, v86, v42, v43
	v_max3_f32 v86, v86, v44, v45
	v_max3_f32 v86, v86, v46, v47
	v_max3_f32 v86, v86, v48, v49
	v_mov_b32_e32 v87, v86
	s_nop 1
	v_permlane32_swap_b32_e32 v86, v87
	v_max_f32_e32 v87, v87, v87
	v_max_f32_e32 v86, v86, v86
	v_max_f32_e32 v86, v86, v87
	v_cmp_lt_f32_e64 s[40:41], s70, v86
	v_cmp_lt_f32_e64 s[4:5], s84, v86
	s_orn2_b64 s[4:5], s[4:5], s[38:39]
	s_and_b64 s[4:5], s[4:5], s[40:41]
	s_cbranch_scc0 .LBB0_1061
	v_max_f32_e32 v86, v86, v86
	v_max_f32_e32 v86, 0xc2700000, v86
	v_cndmask_b32_e64 v86, 0, v86, s[4:5]
	v_exp_f32_e64 v88, -v86
	v_add_f32_e32 v183, v183, v86
	v_pk_add_f32 v[34:35], v[34:35], v[86:87] op_sel_hi:[1,0] neg_lo:[0,1] neg_hi:[0,1]
	v_pk_add_f32 v[36:37], v[36:37], v[86:87] op_sel_hi:[1,0] neg_lo:[0,1] neg_hi:[0,1]
	v_mul_f32_e32 v1, v1, v88
	v_pk_add_f32 v[38:39], v[38:39], v[86:87] op_sel_hi:[1,0] neg_lo:[0,1] neg_hi:[0,1]
	v_pk_add_f32 v[40:41], v[40:41], v[86:87] op_sel_hi:[1,0] neg_lo:[0,1] neg_hi:[0,1]
	v_pk_add_f32 v[42:43], v[42:43], v[86:87] op_sel_hi:[1,0] neg_lo:[0,1] neg_hi:[0,1]
	v_pk_add_f32 v[44:45], v[44:45], v[86:87] op_sel_hi:[1,0] neg_lo:[0,1] neg_hi:[0,1]
	v_pk_add_f32 v[46:47], v[46:47], v[86:87] op_sel_hi:[1,0] neg_lo:[0,1] neg_hi:[0,1]
	v_pk_mul_f32 v[32:33], v[32:33], v[88:89] op_sel_hi:[1,0]
	v_pk_mul_f32 v[30:31], v[30:31], v[88:89] op_sel_hi:[1,0]
	v_pk_mul_f32 v[28:29], v[28:29], v[88:89] op_sel_hi:[1,0]
	v_pk_mul_f32 v[26:27], v[26:27], v[88:89] op_sel_hi:[1,0]
	v_pk_mul_f32 v[24:25], v[24:25], v[88:89] op_sel_hi:[1,0]
	v_pk_mul_f32 v[22:23], v[22:23], v[88:89] op_sel_hi:[1,0]
	v_pk_mul_f32 v[20:21], v[20:21], v[88:89] op_sel_hi:[1,0]
	v_pk_mul_f32 v[18:19], v[18:19], v[88:89] op_sel_hi:[1,0]
	v_pk_mul_f32 v[16:17], v[16:17], v[88:89] op_sel_hi:[1,0]
	v_pk_mul_f32 v[14:15], v[14:15], v[88:89] op_sel_hi:[1,0]
	v_pk_mul_f32 v[12:13], v[12:13], v[88:89] op_sel_hi:[1,0]
	v_pk_mul_f32 v[10:11], v[10:11], v[88:89] op_sel_hi:[1,0]
	v_pk_mul_f32 v[8:9], v[8:9], v[88:89] op_sel_hi:[1,0]
	v_pk_mul_f32 v[6:7], v[6:7], v[88:89] op_sel_hi:[1,0]
	v_pk_mul_f32 v[4:5], v[4:5], v[88:89] op_sel_hi:[1,0]
	v_pk_mul_f32 v[2:3], v[2:3], v[88:89] op_sel_hi:[1,0]
	v_pk_add_f32 v[48:49], v[48:49], v[86:87] op_sel_hi:[1,0] neg_lo:[0,1] neg_hi:[0,1]

; DI float fast_exp2(float x) { return __builtin_amdgcn_exp2f(x); }
; #define MFMA32(a, b, c) __builtin_amdgcn_mfma_f32_32x32x16_bf16((a), (b), (c), 0, 0, 0)
; DI int crow(int r, int hi) { return (r & 3) + 8 * (r >> 2) + 4 * hi; }
; DI float xhalf_max(float v) { const auto rr = __builtin_amdgcn_permlane32_swap(__float_as_uint(v), __float_as_uint(v), false, false); return fmaxf(__uint_as_float(rr[0]), __uint_as_float(rr[1])); }
; DI int ccol(int r) { return (r & 3) + 8 * (r >> 2); }
; DI void frag_scores(f32x16& x0, const KFrag& K0, const bf16x8 (&qf)[4], float sk, float aref, int p0, bool needmask, int lo, int hip, int hi) {
;     const float B = fmaf(sk, (float)(p0 + 4 * hi), -aref);
; #pragma unroll
;     for (int r = 0; r < 16; ++r) x0[r] = fmaf(sk, (float)ccol(r), B);
; #pragma unroll
;     for (int d0 = 0; d0 < 4; ++d0) x0 = MFMA32(K0.k[d0], qf[d0], x0);
;     if (needmask) {
; #pragma unroll
;         for (int r = 0; r < 16; ++r) { const int pos = p0 + crow(r, hi); if (pos < lo || pos > hip) x0[r] = -1e30f; }
;     }
; }
; DI void soft_update1(Soft& f, f32x16& x0) {
;     float mx = x0[0];
; #pragma unroll
;     for (int r = 1; r < 16; ++r) mx = fmaxf(mx, x0[r]);
;     mx = xhalf_max(mx);
;     const bool valid = mx > -1e20f;
;     const bool need = valid && (mx > 8.f || !f.seen);
;     if (__builtin_amdgcn_ballot_w64(need)) {
;         const float delta = need ? fmaxf(mx, -60.f) : 0.f; const float sc = fast_exp2(-delta);
;         f.mref += delta; f.l *= sc;
; #pragma unroll
;         for (int r = 0; r < 16; ++r) { f.o0[r] *= sc; f.o1[r] *= sc; x0[r] -= delta; }
;     }
.LBB0_1064:
	v_add_u32_e32 v34, 0xffffffa0, v181
	v_cvt_f32_u32_e32 v34, v34
	v_add_f32_e32 v35, v182, v183
	s_mov_b64 s[4:5], 0
	v_fma_f32 v48, v168, v34, -v35
	v_fma_f32 v34, 0, v168, v48
	v_add_f32_e32 v35, v168, v48
	v_pk_fma_f32 v[36:37], v[168:169], s[82:83], v[48:49] op_sel_hi:[1,1,0]
	v_pk_fma_f32 v[38:39], v[168:169], s[84:85], v[48:49] op_sel_hi:[1,1,0]
	v_pk_fma_f32 v[40:41], v[168:169], s[86:87], v[48:49] op_sel_hi:[1,1,0]
	v_pk_fma_f32 v[42:43], v[168:169], s[80:81], v[48:49] op_sel_hi:[1,1,0]
	v_pk_fma_f32 v[44:45], v[168:169], s[88:89], v[48:49] op_sel_hi:[1,1,0]
	v_pk_fma_f32 v[46:47], v[168:169], s[90:91], v[48:49] op_sel_hi:[1,1,0]
	v_pk_fma_f32 v[48:49], v[168:169], s[92:93], v[48:49] op_sel_hi:[1,1,0]
	s_waitcnt vmcnt(23)
	s_nop 0
	v_mfma_f32_32x32x16_bf16 v[34:49], v[142:145], v[50:53], v[34:49]
	s_waitcnt vmcnt(22)
	v_mfma_f32_32x32x16_bf16 v[34:49], v[138:141], v[54:57], v[34:49]
	s_waitcnt vmcnt(21)
	v_mfma_f32_32x32x16_bf16 v[34:49], v[134:137], v[58:61], v[34:49]
	s_waitcnt vmcnt(20)
	v_mfma_f32_32x32x16_bf16 v[34:49], v[130:133], v[62:65], v[34:49]
	s_nop 11
	v_max_f32_e32 v66, v35, v35
	v_max_f32_e32 v67, v34, v34
	v_max_f32_e32 v66, v67, v66
	v_max3_f32 v66, v66, v36, v37
	v_max3_f32 v66, v66, v38, v39
	v_max3_f32 v66, v66, v40, v41
	v_max3_f32 v66, v66, v42, v43
	v_max3_f32 v66, v66, v44, v45
	v_max3_f32 v66, v66, v46, v47
	v_max3_f32 v66, v66, v48, v49
	v_mov_b32_e32 v67, v66
	s_nop 1
	v_permlane32_swap_b32_e32 v66, v67
	v_max_f32_e32 v67, v67, v67
	v_max_f32_e32 v66, v66, v66
	v_max_f32_e32 v66, v66, v67
	v_cmp_lt_f32_e64 s[40:41], s70, v66
	v_cmp_lt_f32_e64 s[4:5], s84, v66
	s_orn2_b64 s[4:5], s[4:5], s[38:39]
	s_and_b64 s[4:5], s[4:5], s[40:41]
	s_cbranch_scc0 .LBB0_1070
	v_max_f32_e32 v66, v66, v66
	v_max_f32_e32 v66, 0xc2700000, v66
	v_cndmask_b32_e64 v66, 0, v66, s[4:5]
	v_exp_f32_e64 v68, -v66
	v_add_f32_e32 v183, v183, v66
	v_pk_add_f32 v[34:35], v[34:35], v[66:67] op_sel_hi:[1,0] neg_lo:[0,1] neg_hi:[0,1]
	v_pk_add_f32 v[36:37], v[36:37], v[66:67] op_sel_hi:[1,0] neg_lo:[0,1] neg_hi:[0,1]
	v_mul_f32_e32 v1, v1, v68
	v_pk_add_f32 v[38:39], v[38:39], v[66:67] op_sel_hi:[1,0] neg_lo:[0,1] neg_hi:[0,1]
	v_pk_add_f32 v[40:41], v[40:41], v[66:67] op_sel_hi:[1,0] neg_lo:[0,1] neg_hi:[0,1]
	v_pk_add_f32 v[42:43], v[42:43], v[66:67] op_sel_hi:[1,0] neg_lo:[0,1] neg_hi:[0,1]
	v_pk_add_f32 v[44:45], v[44:45], v[66:67] op_sel_hi:[1,0] neg_lo:[0,1] neg_hi:[0,1]
	v_pk_add_f32 v[46:47], v[46:47], v[66:67] op_sel_hi:[1,0] neg_lo:[0,1] neg_hi:[0,1]
	v_pk_mul_f32 v[32:33], v[32:33], v[68:69] op_sel_hi:[1,0]
	v_pk_mul_f32 v[30:31], v[30:31], v[68:69] op_sel_hi:[1,0]
	v_pk_mul_f32 v[28:29], v[28:29], v[68:69] op_sel_hi:[1,0]
	v_pk_mul_f32 v[26:27], v[26:27], v[68:69] op_sel_hi:[1,0]
	v_pk_mul_f32 v[24:25], v[24:25], v[68:69] op_sel_hi:[1,0]
	v_pk_mul_f32 v[22:23], v[22:23], v[68:69] op_sel_hi:[1,0]
	v_pk_mul_f32 v[20:21], v[20:21], v[68:69] op_sel_hi:[1,0]
	v_pk_mul_f32 v[18:19], v[18:19], v[68:69] op_sel_hi:[1,0]
	v_pk_mul_f32 v[16:17], v[16:17], v[68:69] op_sel_hi:[1,0]
	v_pk_mul_f32 v[14:15], v[14:15], v[68:69] op_sel_hi:[1,0]
	v_pk_mul_f32 v[12:13], v[12:13], v[68:69] op_sel_hi:[1,0]
	v_pk_mul_f32 v[10:11], v[10:11], v[68:69] op_sel_hi:[1,0]
	v_pk_mul_f32 v[8:9], v[8:9], v[68:69] op_sel_hi:[1,0]
	v_pk_mul_f32 v[6:7], v[6:7], v[68:69] op_sel_hi:[1,0]
	v_pk_mul_f32 v[4:5], v[4:5], v[68:69] op_sel_hi:[1,0]
	v_pk_mul_f32 v[2:3], v[2:3], v[68:69] op_sel_hi:[1,0]
	v_pk_add_f32 v[48:49], v[48:49], v[66:67] op_sel_hi:[1,0] neg_lo:[0,1] neg_hi:[0,1]
